# side-job cache conversion: coalesced 32-byte source reads, swizzle applied on the store side
# baseline (speedup 1.0000x reference)
; DEVI u32x4 pack8(const f32x4 a, const f32x4 b) { u32x4 w; w.x = cvtpk(a[0], a[1]); w.y = cvtpk(a[2], a[3]); w.z = cvtpk(b[0], b[1]); w.w = cvtpk(b[2], b[3]); return w; }
; DEVI const float* IN(int i) { return *(const float* const __attribute__((address_space(4)))*)(kargs() + 8 * i); }
; DEVI void prologue(int wv, LAS unsigned char* lds) {
;     ...
;         const float* cache_ckv = IN(2); bf16_t* ckvb = (bf16_t*)(ws + O_CKVB);
;         for (size_t i = gt; i < (size_t)2 * MC * 256 / 8; i += 8 * NGT) {
;             f32x4 a[8], b[8];
; #pragma unroll
;             for (int k = 0; k < 8; ++k) { const size_t ii = i + k * NGT; if (ii < (size_t)2 * MC * 256 / 8) { a[k] = *(const f32x4*)(cache_ckv + ii * 8); b[k] = *(const f32x4*)(cache_ckv + ii * 8 + 4); } }
; #pragma unroll
;             for (int k = 0; k < 8; ++k) { const size_t ii = i + k * NGT; if (ii < (size_t)2 * MC * 256 / 8) *(u32x4*)(ckvb + ii * 8) = pack8(a[k], b[k]); }
;         }
.Lsjd_loop1_1:
	v_mov_b32_e32 v1, v0
	v_cmp_gt_u32_e64 s[12:13], s10, v1
	v_add_u32_e32 v2, 0xcc00, v0
	v_cmp_gt_u32_e64 s[14:15], s10, v2
	v_add_u32_e32 v3, 0x19800, v0
	v_cmp_gt_u32_e64 s[16:17], s10, v3
	v_add_u32_e32 v4, 0x26400, v0
	v_cmp_gt_u32_e64 s[18:19], s10, v4
	v_add_u32_e32 v5, 0x33000, v0
	v_cmp_gt_u32_e64 s[20:21], s10, v5
	v_add_u32_e32 v6, 0x3fc00, v0
	v_cmp_gt_u32_e64 s[22:23], s10, v6
	v_add_u32_e32 v7, 0x4c800, v0
	v_cmp_gt_u32_e64 s[24:25], s10, v7
	v_add_u32_e32 v8, 0x59400, v0
	v_cmp_gt_u32_e64 s[26:27], s10, v8
	s_mov_b64 exec, s[12:13]
	v_lshlrev_b32_e32 v9, 5, v1
	global_load_dwordx4 v[24:27], v9, s[6:7]
	global_load_dwordx4 v[28:31], v9, s[6:7] offset:16
	s_mov_b64 exec, s[14:15]
	v_lshlrev_b32_e32 v10, 5, v2
	global_load_dwordx4 v[32:35], v10, s[6:7]
	global_load_dwordx4 v[36:39], v10, s[6:7] offset:16
	s_mov_b64 exec, s[16:17]
	v_lshlrev_b32_e32 v11, 5, v3
	global_load_dwordx4 v[40:43], v11, s[6:7]
	global_load_dwordx4 v[44:47], v11, s[6:7] offset:16
	s_mov_b64 exec, s[18:19]
	v_lshlrev_b32_e32 v12, 5, v4
	global_load_dwordx4 v[48:51], v12, s[6:7]
	global_load_dwordx4 v[52:55], v12, s[6:7] offset:16
	s_mov_b64 exec, s[20:21]
	v_lshlrev_b32_e32 v13, 5, v5
	global_load_dwordx4 v[56:59], v13, s[6:7]
	global_load_dwordx4 v[60:63], v13, s[6:7] offset:16
	s_mov_b64 exec, s[22:23]
	v_lshlrev_b32_e32 v14, 5, v6
	global_load_dwordx4 v[64:67], v14, s[6:7]
	global_load_dwordx4 v[68:71], v14, s[6:7] offset:16
	s_mov_b64 exec, s[24:25]
	v_lshlrev_b32_e32 v15, 5, v7
	global_load_dwordx4 v[72:75], v15, s[6:7]
	global_load_dwordx4 v[76:79], v15, s[6:7] offset:16
	s_mov_b64 exec, s[26:27]
	v_lshlrev_b32_e32 v16, 5, v8
	global_load_dwordx4 v[80:83], v16, s[6:7]
	global_load_dwordx4 v[84:87], v16, s[6:7] offset:16
	s_mov_b64 exec, s[12:13]
	v_and_b32_e32 v20, 0x3ff, v1
	v_and_b32_e32 v21, 0xfffffc00, v1
	v_lshrrev_b32_e32 v22, 5, v20
	v_or_b32_e32 v21, v21, v22
	v_bfe_u32 v22, v20, 3, 2
	v_lshl_or_b32 v21, v22, 8, v21
	v_bfe_u32 v22, v20, 2, 1
	v_lshl_or_b32 v21, v22, 5, v21
	v_and_b32_e32 v22, 3, v20
	v_lshl_or_b32 v21, v22, 6, v21
	s_waitcnt vmcnt(14)
	v_cvt_pk_bf16_f32 v100, v24, v25
	v_cvt_pk_bf16_f32 v101, v26, v27
	v_cvt_pk_bf16_f32 v102, v28, v29
	v_cvt_pk_bf16_f32 v103, v30, v31
	v_lshlrev_b32_e32 v104, 4, v21
	global_store_dwordx4 v104, v[100:103], s[8:9]
	s_mov_b64 exec, s[14:15]
	v_and_b32_e32 v20, 0x3ff, v2
	v_and_b32_e32 v21, 0xfffffc00, v2
	v_lshrrev_b32_e32 v22, 5, v20
	v_or_b32_e32 v21, v21, v22
	v_bfe_u32 v22, v20, 3, 2
	v_lshl_or_b32 v21, v22, 8, v21
	v_bfe_u32 v22, v20, 2, 1
	v_lshl_or_b32 v21, v22, 5, v21
	v_and_b32_e32 v22, 3, v20
	v_lshl_or_b32 v21, v22, 6, v21
	s_waitcnt vmcnt(12)
	v_cvt_pk_bf16_f32 v106, v32, v33
	v_cvt_pk_bf16_f32 v107, v34, v35
	v_cvt_pk_bf16_f32 v108, v36, v37
	v_cvt_pk_bf16_f32 v109, v38, v39
	v_lshlrev_b32_e32 v110, 4, v21
	global_store_dwordx4 v110, v[106:109], s[8:9]
	s_mov_b64 exec, s[16:17]
	v_and_b32_e32 v20, 0x3ff, v3
	v_and_b32_e32 v21, 0xfffffc00, v3
	v_lshrrev_b32_e32 v22, 5, v20
	v_or_b32_e32 v21, v21, v22
	v_bfe_u32 v22, v20, 3, 2
	v_lshl_or_b32 v21, v22, 8, v21
	v_bfe_u32 v22, v20, 2, 1
	v_lshl_or_b32 v21, v22, 5, v21
	v_and_b32_e32 v22, 3, v20
	v_lshl_or_b32 v21, v22, 6, v21
	s_waitcnt vmcnt(10)
	v_cvt_pk_bf16_f32 v100, v40, v41
	v_cvt_pk_bf16_f32 v101, v42, v43
	v_cvt_pk_bf16_f32 v102, v44, v45
	v_cvt_pk_bf16_f32 v103, v46, v47
	v_lshlrev_b32_e32 v104, 4, v21
	global_store_dwordx4 v104, v[100:103], s[8:9]
	s_mov_b64 exec, s[18:19]
	v_and_b32_e32 v20, 0x3ff, v4
	v_and_b32_e32 v21, 0xfffffc00, v4
	v_lshrrev_b32_e32 v22, 5, v20
	v_or_b32_e32 v21, v21, v22
	v_bfe_u32 v22, v20, 3, 2
	v_lshl_or_b32 v21, v22, 8, v21
	v_bfe_u32 v22, v20, 2, 1
	v_lshl_or_b32 v21, v22, 5, v21
	v_and_b32_e32 v22, 3, v20
	v_lshl_or_b32 v21, v22, 6, v21
	s_waitcnt vmcnt(8)
	v_cvt_pk_bf16_f32 v106, v48, v49
	v_cvt_pk_bf16_f32 v107, v50, v51
	v_cvt_pk_bf16_f32 v108, v52, v53
	v_cvt_pk_bf16_f32 v109, v54, v55
	v_lshlrev_b32_e32 v110, 4, v21
	global_store_dwordx4 v110, v[106:109], s[8:9]
	s_mov_b64 exec, s[20:21]
	v_and_b32_e32 v20, 0x3ff, v5
	v_and_b32_e32 v21, 0xfffffc00, v5
	v_lshrrev_b32_e32 v22, 5, v20
	v_or_b32_e32 v21, v21, v22
	v_bfe_u32 v22, v20, 3, 2
	v_lshl_or_b32 v21, v22, 8, v21
	v_bfe_u32 v22, v20, 2, 1
	v_lshl_or_b32 v21, v22, 5, v21
	v_and_b32_e32 v22, 3, v20
	v_lshl_or_b32 v21, v22, 6, v21
	s_waitcnt vmcnt(6)
	v_cvt_pk_bf16_f32 v100, v56, v57
	v_cvt_pk_bf16_f32 v101, v58, v59
	v_cvt_pk_bf16_f32 v102, v60, v61
	v_cvt_pk_bf16_f32 v103, v62, v63
	v_lshlrev_b32_e32 v104, 4, v21
	global_store_dwordx4 v104, v[100:103], s[8:9]
	s_mov_b64 exec, s[22:23]
	v_and_b32_e32 v20, 0x3ff, v6
	v_and_b32_e32 v21, 0xfffffc00, v6
	v_lshrrev_b32_e32 v22, 5, v20
	v_or_b32_e32 v21, v21, v22
	v_bfe_u32 v22, v20, 3, 2
	v_lshl_or_b32 v21, v22, 8, v21
	v_bfe_u32 v22, v20, 2, 1
	v_lshl_or_b32 v21, v22, 5, v21
	v_and_b32_e32 v22, 3, v20
	v_lshl_or_b32 v21, v22, 6, v21
	s_waitcnt vmcnt(4)
	v_cvt_pk_bf16_f32 v106, v64, v65
	v_cvt_pk_bf16_f32 v107, v66, v67
	v_cvt_pk_bf16_f32 v108, v68, v69
	v_cvt_pk_bf16_f32 v109, v70, v71
	v_lshlrev_b32_e32 v110, 4, v21
	global_store_dwordx4 v110, v[106:109], s[8:9]
	s_mov_b64 exec, s[24:25]
	v_and_b32_e32 v20, 0x3ff, v7
	v_and_b32_e32 v21, 0xfffffc00, v7
	v_lshrrev_b32_e32 v22, 5, v20
	v_or_b32_e32 v21, v21, v22
	v_bfe_u32 v22, v20, 3, 2
	v_lshl_or_b32 v21, v22, 8, v21
	v_bfe_u32 v22, v20, 2, 1
	v_lshl_or_b32 v21, v22, 5, v21
	v_and_b32_e32 v22, 3, v20
	v_lshl_or_b32 v21, v22, 6, v21
	s_waitcnt vmcnt(2)
	v_cvt_pk_bf16_f32 v100, v72, v73
	v_cvt_pk_bf16_f32 v101, v74, v75
	v_cvt_pk_bf16_f32 v102, v76, v77
	v_cvt_pk_bf16_f32 v103, v78, v79
	v_lshlrev_b32_e32 v104, 4, v21
	global_store_dwordx4 v104, v[100:103], s[8:9]
	s_mov_b64 exec, s[26:27]
	v_and_b32_e32 v20, 0x3ff, v8
	v_and_b32_e32 v21, 0xfffffc00, v8
	v_lshrrev_b32_e32 v22, 5, v20
	v_or_b32_e32 v21, v21, v22
	v_bfe_u32 v22, v20, 3, 2
	v_lshl_or_b32 v21, v22, 8, v21
	v_bfe_u32 v22, v20, 2, 1
	v_lshl_or_b32 v21, v22, 5, v21
	v_and_b32_e32 v22, 3, v20
	v_lshl_or_b32 v21, v22, 6, v21
	s_waitcnt vmcnt(0)
	v_cvt_pk_bf16_f32 v106, v80, v81
	v_cvt_pk_bf16_f32 v107, v82, v83
	v_cvt_pk_bf16_f32 v108, v84, v85
	v_cvt_pk_bf16_f32 v109, v86, v87
	v_lshlrev_b32_e32 v110, 4, v21
	global_store_dwordx4 v110, v[106:109], s[8:9]
	s_mov_b64 exec, -1
	v_add_u32_e32 v0, 0x66000, v0
	v_cmp_gt_u32_e32 vcc, s10, v0
	s_and_b64 vcc, exec, vcc
	s_cbranch_scc1 .Lsjd_loop1_1

; DEVI u32x4 pack8(const f32x4 a, const f32x4 b) { u32x4 w; w.x = cvtpk(a[0], a[1]); w.y = cvtpk(a[2], a[3]); w.z = cvtpk(b[0], b[1]); w.w = cvtpk(b[2], b[3]); return w; }
; DEVI const float* IN(int i) { return *(const float* const __attribute__((address_space(4)))*)(kargs() + 8 * i); }
; DEVI void prologue(int wv, LAS unsigned char* lds) {
;     ...
;     {
;         const float* cache_ckv = IN(2); bf16_t* ckvb = (bf16_t*)(ws + O_CKVB);
;         for (size_t i = gt; i < (size_t)2 * MC * 256 / 8; i += 8 * NGT) {
;             f32x4 a[8], b[8];
; #pragma unroll
;             for (int k = 0; k < 8; ++k) { const size_t ii = i + k * NGT; if (ii < (size_t)2 * MC * 256 / 8) { a[k] = *(const f32x4*)(cache_ckv + ii * 8); b[k] = *(const f32x4*)(cache_ckv + ii * 8 + 4); } }
; #pragma unroll
;             for (int k = 0; k < 8; ++k) { const size_t ii = i + k * NGT; if (ii < (size_t)2 * MC * 256 / 8) *(u32x4*)(ckvb + ii * 8) = pack8(a[k], b[k]); }
;         }
;     }
.Lsjd_loop4_0:
	v_mov_b32_e32 v1, v0
	v_cmp_gt_u32_e64 s[12:13], s10, v1
	v_add_u32_e32 v2, 0x1f000, v0
	v_cmp_gt_u32_e64 s[14:15], s10, v2
	v_add_u32_e32 v3, 0x3e000, v0
	v_cmp_gt_u32_e64 s[16:17], s10, v3
	v_add_u32_e32 v4, 0x5d000, v0
	v_cmp_gt_u32_e64 s[18:19], s10, v4
	v_add_u32_e32 v5, 0x7c000, v0
	v_cmp_gt_u32_e64 s[20:21], s10, v5
	v_add_u32_e32 v6, 0x9b000, v0
	v_cmp_gt_u32_e64 s[22:23], s10, v6
	v_add_u32_e32 v7, 0xba000, v0
	v_cmp_gt_u32_e64 s[24:25], s10, v7
	v_add_u32_e32 v8, 0xd9000, v0
	v_cmp_gt_u32_e64 s[26:27], s10, v8
	s_mov_b64 exec, s[12:13]
	v_lshlrev_b32_e32 v9, 5, v1
	global_load_dwordx4 v[24:27], v9, s[6:7]
	global_load_dwordx4 v[28:31], v9, s[6:7] offset:16
	s_mov_b64 exec, s[14:15]
	v_lshlrev_b32_e32 v10, 5, v2
	global_load_dwordx4 v[32:35], v10, s[6:7]
	global_load_dwordx4 v[36:39], v10, s[6:7] offset:16
	s_mov_b64 exec, s[16:17]
	v_lshlrev_b32_e32 v11, 5, v3
	global_load_dwordx4 v[40:43], v11, s[6:7]
	global_load_dwordx4 v[44:47], v11, s[6:7] offset:16
	s_mov_b64 exec, s[18:19]
	v_lshlrev_b32_e32 v12, 5, v4
	global_load_dwordx4 v[48:51], v12, s[6:7]
	global_load_dwordx4 v[52:55], v12, s[6:7] offset:16
	s_mov_b64 exec, s[20:21]
	v_lshlrev_b32_e32 v13, 5, v5
	global_load_dwordx4 v[56:59], v13, s[6:7]
	global_load_dwordx4 v[60:63], v13, s[6:7] offset:16
	s_mov_b64 exec, s[22:23]
	v_lshlrev_b32_e32 v14, 5, v6
	global_load_dwordx4 v[64:67], v14, s[6:7]
	global_load_dwordx4 v[68:71], v14, s[6:7] offset:16
	s_mov_b64 exec, s[24:25]
	v_lshlrev_b32_e32 v15, 5, v7
	global_load_dwordx4 v[72:75], v15, s[6:7]
	global_load_dwordx4 v[76:79], v15, s[6:7] offset:16
	s_mov_b64 exec, s[26:27]
	v_lshlrev_b32_e32 v16, 5, v8
	global_load_dwordx4 v[80:83], v16, s[6:7]
	global_load_dwordx4 v[84:87], v16, s[6:7] offset:16
	s_mov_b64 exec, s[12:13]
	v_and_b32_e32 v20, 0x3ff, v1
	v_and_b32_e32 v21, 0xfffffc00, v1
	v_lshrrev_b32_e32 v22, 5, v20
	v_or_b32_e32 v21, v21, v22
	v_bfe_u32 v22, v20, 3, 2
	v_lshl_or_b32 v21, v22, 8, v21
	v_bfe_u32 v22, v20, 2, 1
	v_lshl_or_b32 v21, v22, 5, v21
	v_and_b32_e32 v22, 3, v20
	v_lshl_or_b32 v21, v22, 6, v21
	s_waitcnt vmcnt(14)
	v_cvt_pk_bf16_f32 v100, v24, v25
	v_cvt_pk_bf16_f32 v101, v26, v27
	v_cvt_pk_bf16_f32 v102, v28, v29
	v_cvt_pk_bf16_f32 v103, v30, v31
	v_lshlrev_b32_e32 v104, 4, v21
	global_store_dwordx4 v104, v[100:103], s[8:9]
	s_mov_b64 exec, s[14:15]
	v_and_b32_e32 v20, 0x3ff, v2
	v_and_b32_e32 v21, 0xfffffc00, v2
	v_lshrrev_b32_e32 v22, 5, v20
	v_or_b32_e32 v21, v21, v22
	v_bfe_u32 v22, v20, 3, 2
	v_lshl_or_b32 v21, v22, 8, v21
	v_bfe_u32 v22, v20, 2, 1
	v_lshl_or_b32 v21, v22, 5, v21
	v_and_b32_e32 v22, 3, v20
	v_lshl_or_b32 v21, v22, 6, v21
	s_waitcnt vmcnt(12)
	v_cvt_pk_bf16_f32 v106, v32, v33
	v_cvt_pk_bf16_f32 v107, v34, v35
	v_cvt_pk_bf16_f32 v108, v36, v37
	v_cvt_pk_bf16_f32 v109, v38, v39
	v_lshlrev_b32_e32 v110, 4, v21
	global_store_dwordx4 v110, v[106:109], s[8:9]
	s_mov_b64 exec, s[16:17]
	v_and_b32_e32 v20, 0x3ff, v3
	v_and_b32_e32 v21, 0xfffffc00, v3
	v_lshrrev_b32_e32 v22, 5, v20
	v_or_b32_e32 v21, v21, v22
	v_bfe_u32 v22, v20, 3, 2
	v_lshl_or_b32 v21, v22, 8, v21
	v_bfe_u32 v22, v20, 2, 1
	v_lshl_or_b32 v21, v22, 5, v21
	v_and_b32_e32 v22, 3, v20
	v_lshl_or_b32 v21, v22, 6, v21
	s_waitcnt vmcnt(10)
	v_cvt_pk_bf16_f32 v100, v40, v41
	v_cvt_pk_bf16_f32 v101, v42, v43
	v_cvt_pk_bf16_f32 v102, v44, v45
	v_cvt_pk_bf16_f32 v103, v46, v47
	v_lshlrev_b32_e32 v104, 4, v21
	global_store_dwordx4 v104, v[100:103], s[8:9]
	s_mov_b64 exec, s[18:19]
	v_and_b32_e32 v20, 0x3ff, v4
	v_and_b32_e32 v21, 0xfffffc00, v4
	v_lshrrev_b32_e32 v22, 5, v20
	v_or_b32_e32 v21, v21, v22
	v_bfe_u32 v22, v20, 3, 2
	v_lshl_or_b32 v21, v22, 8, v21
	v_bfe_u32 v22, v20, 2, 1
	v_lshl_or_b32 v21, v22, 5, v21
	v_and_b32_e32 v22, 3, v20
	v_lshl_or_b32 v21, v22, 6, v21
	s_waitcnt vmcnt(8)
	v_cvt_pk_bf16_f32 v106, v48, v49
	v_cvt_pk_bf16_f32 v107, v50, v51
	v_cvt_pk_bf16_f32 v108, v52, v53
	v_cvt_pk_bf16_f32 v109, v54, v55
	v_lshlrev_b32_e32 v110, 4, v21
	global_store_dwordx4 v110, v[106:109], s[8:9]
	s_mov_b64 exec, s[20:21]
	v_and_b32_e32 v20, 0x3ff, v5
	v_and_b32_e32 v21, 0xfffffc00, v5
	v_lshrrev_b32_e32 v22, 5, v20
	v_or_b32_e32 v21, v21, v22
	v_bfe_u32 v22, v20, 3, 2
	v_lshl_or_b32 v21, v22, 8, v21
	v_bfe_u32 v22, v20, 2, 1
	v_lshl_or_b32 v21, v22, 5, v21
	v_and_b32_e32 v22, 3, v20
	v_lshl_or_b32 v21, v22, 6, v21
	s_waitcnt vmcnt(6)
	v_cvt_pk_bf16_f32 v100, v56, v57
	v_cvt_pk_bf16_f32 v101, v58, v59
	v_cvt_pk_bf16_f32 v102, v60, v61
	v_cvt_pk_bf16_f32 v103, v62, v63
	v_lshlrev_b32_e32 v104, 4, v21
	global_store_dwordx4 v104, v[100:103], s[8:9]
	s_mov_b64 exec, s[22:23]
	v_and_b32_e32 v20, 0x3ff, v6
	v_and_b32_e32 v21, 0xfffffc00, v6
	v_lshrrev_b32_e32 v22, 5, v20
	v_or_b32_e32 v21, v21, v22
	v_bfe_u32 v22, v20, 3, 2
	v_lshl_or_b32 v21, v22, 8, v21
	v_bfe_u32 v22, v20, 2, 1
	v_lshl_or_b32 v21, v22, 5, v21
	v_and_b32_e32 v22, 3, v20
	v_lshl_or_b32 v21, v22, 6, v21
	s_waitcnt vmcnt(4)
	v_cvt_pk_bf16_f32 v106, v64, v65
	v_cvt_pk_bf16_f32 v107, v66, v67
	v_cvt_pk_bf16_f32 v108, v68, v69
	v_cvt_pk_bf16_f32 v109, v70, v71
	v_lshlrev_b32_e32 v110, 4, v21
	global_store_dwordx4 v110, v[106:109], s[8:9]
	s_mov_b64 exec, s[24:25]
	v_and_b32_e32 v20, 0x3ff, v7
	v_and_b32_e32 v21, 0xfffffc00, v7
	v_lshrrev_b32_e32 v22, 5, v20
	v_or_b32_e32 v21, v21, v22
	v_bfe_u32 v22, v20, 3, 2
	v_lshl_or_b32 v21, v22, 8, v21
	v_bfe_u32 v22, v20, 2, 1
	v_lshl_or_b32 v21, v22, 5, v21
	v_and_b32_e32 v22, 3, v20
	v_lshl_or_b32 v21, v22, 6, v21
	s_waitcnt vmcnt(2)
	v_cvt_pk_bf16_f32 v100, v72, v73
	v_cvt_pk_bf16_f32 v101, v74, v75
	v_cvt_pk_bf16_f32 v102, v76, v77
	v_cvt_pk_bf16_f32 v103, v78, v79
	v_lshlrev_b32_e32 v104, 4, v21
	global_store_dwordx4 v104, v[100:103], s[8:9]
	s_mov_b64 exec, s[26:27]
	v_and_b32_e32 v20, 0x3ff, v8
	v_and_b32_e32 v21, 0xfffffc00, v8
	v_lshrrev_b32_e32 v22, 5, v20
	v_or_b32_e32 v21, v21, v22
	v_bfe_u32 v22, v20, 3, 2
	v_lshl_or_b32 v21, v22, 8, v21
	v_bfe_u32 v22, v20, 2, 1
	v_lshl_or_b32 v21, v22, 5, v21
	v_and_b32_e32 v22, 3, v20
	v_lshl_or_b32 v21, v22, 6, v21
	s_waitcnt vmcnt(0)
	v_cvt_pk_bf16_f32 v106, v80, v81
	v_cvt_pk_bf16_f32 v107, v82, v83
	v_cvt_pk_bf16_f32 v108, v84, v85
	v_cvt_pk_bf16_f32 v109, v86, v87
	v_lshlrev_b32_e32 v110, 4, v21
	global_store_dwordx4 v110, v[106:109], s[8:9]
	s_mov_b64 exec, -1
	v_add_u32_e32 v0, 0xf8000, v0
	v_cmp_gt_u32_e32 vcc, s10, v0
	s_and_b64 vcc, exec, vcc
	s_cbranch_scc1 .Lsjd_loop4_0

; DEVI u32x4 pack8(const f32x4 a, const f32x4 b) { u32x4 w; w.x = cvtpk(a[0], a[1]); w.y = cvtpk(a[2], a[3]); w.z = cvtpk(b[0], b[1]); w.w = cvtpk(b[2], b[3]); return w; }
; DEVI const float* IN(int i) { return *(const float* const __attribute__((address_space(4)))*)(kargs() + 8 * i); }
; DEVI void prologue(int wv, LAS unsigned char* lds) {
;     ...
;     {
;         const float* cache_ckv = IN(2); bf16_t* ckvb = (bf16_t*)(ws + O_CKVB);
;         for (size_t i = gt; i < (size_t)2 * MC * 256 / 8; i += 8 * NGT) {
;             f32x4 a[8], b[8];
; #pragma unroll
;             for (int k = 0; k < 8; ++k) { const size_t ii = i + k * NGT; if (ii < (size_t)2 * MC * 256 / 8) { a[k] = *(const f32x4*)(cache_ckv + ii * 8); b[k] = *(const f32x4*)(cache_ckv + ii * 8 + 4); } }
; #pragma unroll
;             for (int k = 0; k < 8; ++k) { const size_t ii = i + k * NGT; if (ii < (size_t)2 * MC * 256 / 8) *(u32x4*)(ckvb + ii * 8) = pack8(a[k], b[k]); }
;         }
;     }
.Lsjd_loop6_0:
	v_mov_b32_e32 v1, v0
	v_cmp_gt_u32_e64 s[12:13], s10, v1
	v_add_u32_e32 v2, 0x1c000, v0
	v_cmp_gt_u32_e64 s[14:15], s10, v2
	v_add_u32_e32 v3, 0x38000, v0
	v_cmp_gt_u32_e64 s[16:17], s10, v3
	v_add_u32_e32 v4, 0x54000, v0
	v_cmp_gt_u32_e64 s[18:19], s10, v4
	v_add_u32_e32 v5, 0x70000, v0
	v_cmp_gt_u32_e64 s[20:21], s10, v5
	v_add_u32_e32 v6, 0x8c000, v0
	v_cmp_gt_u32_e64 s[22:23], s10, v6
	v_add_u32_e32 v7, 0xa8000, v0
	v_cmp_gt_u32_e64 s[24:25], s10, v7
	v_add_u32_e32 v8, 0xc4000, v0
	v_cmp_gt_u32_e64 s[26:27], s10, v8
	s_mov_b64 exec, s[12:13]
	v_lshlrev_b32_e32 v9, 5, v1
	global_load_dwordx4 v[24:27], v9, s[6:7]
	global_load_dwordx4 v[28:31], v9, s[6:7] offset:16
	s_mov_b64 exec, s[14:15]
	v_lshlrev_b32_e32 v10, 5, v2
	global_load_dwordx4 v[32:35], v10, s[6:7]
	global_load_dwordx4 v[36:39], v10, s[6:7] offset:16
	s_mov_b64 exec, s[16:17]
	v_lshlrev_b32_e32 v11, 5, v3
	global_load_dwordx4 v[40:43], v11, s[6:7]
	global_load_dwordx4 v[44:47], v11, s[6:7] offset:16
	s_mov_b64 exec, s[18:19]
	v_lshlrev_b32_e32 v12, 5, v4
	global_load_dwordx4 v[48:51], v12, s[6:7]
	global_load_dwordx4 v[52:55], v12, s[6:7] offset:16
	s_mov_b64 exec, s[20:21]
	v_lshlrev_b32_e32 v13, 5, v5
	global_load_dwordx4 v[56:59], v13, s[6:7]
	global_load_dwordx4 v[60:63], v13, s[6:7] offset:16
	s_mov_b64 exec, s[22:23]
	v_lshlrev_b32_e32 v14, 5, v6
	global_load_dwordx4 v[64:67], v14, s[6:7]
	global_load_dwordx4 v[68:71], v14, s[6:7] offset:16
	s_mov_b64 exec, s[24:25]
	v_lshlrev_b32_e32 v15, 5, v7
	global_load_dwordx4 v[72:75], v15, s[6:7]
	global_load_dwordx4 v[76:79], v15, s[6:7] offset:16
	s_mov_b64 exec, s[26:27]
	v_lshlrev_b32_e32 v16, 5, v8
	global_load_dwordx4 v[80:83], v16, s[6:7]
	global_load_dwordx4 v[84:87], v16, s[6:7] offset:16
	s_mov_b64 exec, s[12:13]
	v_and_b32_e32 v20, 0x3ff, v1
	v_and_b32_e32 v21, 0xfffffc00, v1
	v_lshrrev_b32_e32 v22, 5, v20
	v_or_b32_e32 v21, v21, v22
	v_bfe_u32 v22, v20, 3, 2
	v_lshl_or_b32 v21, v22, 8, v21
	v_bfe_u32 v22, v20, 2, 1
	v_lshl_or_b32 v21, v22, 5, v21
	v_and_b32_e32 v22, 3, v20
	v_lshl_or_b32 v21, v22, 6, v21
	s_waitcnt vmcnt(14)
	v_cvt_pk_bf16_f32 v100, v24, v25
	v_cvt_pk_bf16_f32 v101, v26, v27
	v_cvt_pk_bf16_f32 v102, v28, v29
	v_cvt_pk_bf16_f32 v103, v30, v31
	v_lshlrev_b32_e32 v104, 4, v21
	global_store_dwordx4 v104, v[100:103], s[8:9]
	s_mov_b64 exec, s[14:15]
	v_and_b32_e32 v20, 0x3ff, v2
	v_and_b32_e32 v21, 0xfffffc00, v2
	v_lshrrev_b32_e32 v22, 5, v20
	v_or_b32_e32 v21, v21, v22
	v_bfe_u32 v22, v20, 3, 2
	v_lshl_or_b32 v21, v22, 8, v21
	v_bfe_u32 v22, v20, 2, 1
	v_lshl_or_b32 v21, v22, 5, v21
	v_and_b32_e32 v22, 3, v20
	v_lshl_or_b32 v21, v22, 6, v21
	s_waitcnt vmcnt(12)
	v_cvt_pk_bf16_f32 v106, v32, v33
	v_cvt_pk_bf16_f32 v107, v34, v35
	v_cvt_pk_bf16_f32 v108, v36, v37
	v_cvt_pk_bf16_f32 v109, v38, v39
	v_lshlrev_b32_e32 v110, 4, v21
	global_store_dwordx4 v110, v[106:109], s[8:9]
	s_mov_b64 exec, s[16:17]
	v_and_b32_e32 v20, 0x3ff, v3
	v_and_b32_e32 v21, 0xfffffc00, v3
	v_lshrrev_b32_e32 v22, 5, v20
	v_or_b32_e32 v21, v21, v22
	v_bfe_u32 v22, v20, 3, 2
	v_lshl_or_b32 v21, v22, 8, v21
	v_bfe_u32 v22, v20, 2, 1
	v_lshl_or_b32 v21, v22, 5, v21
	v_and_b32_e32 v22, 3, v20
	v_lshl_or_b32 v21, v22, 6, v21
	s_waitcnt vmcnt(10)
	v_cvt_pk_bf16_f32 v100, v40, v41
	v_cvt_pk_bf16_f32 v101, v42, v43
	v_cvt_pk_bf16_f32 v102, v44, v45
	v_cvt_pk_bf16_f32 v103, v46, v47
	v_lshlrev_b32_e32 v104, 4, v21
	global_store_dwordx4 v104, v[100:103], s[8:9]
	s_mov_b64 exec, s[18:19]
	v_and_b32_e32 v20, 0x3ff, v4
	v_and_b32_e32 v21, 0xfffffc00, v4
	v_lshrrev_b32_e32 v22, 5, v20
	v_or_b32_e32 v21, v21, v22
	v_bfe_u32 v22, v20, 3, 2
	v_lshl_or_b32 v21, v22, 8, v21
	v_bfe_u32 v22, v20, 2, 1
	v_lshl_or_b32 v21, v22, 5, v21
	v_and_b32_e32 v22, 3, v20
	v_lshl_or_b32 v21, v22, 6, v21
	s_waitcnt vmcnt(8)
	v_cvt_pk_bf16_f32 v106, v48, v49
	v_cvt_pk_bf16_f32 v107, v50, v51
	v_cvt_pk_bf16_f32 v108, v52, v53
	v_cvt_pk_bf16_f32 v109, v54, v55
	v_lshlrev_b32_e32 v110, 4, v21
	global_store_dwordx4 v110, v[106:109], s[8:9]
	s_mov_b64 exec, s[20:21]
	v_and_b32_e32 v20, 0x3ff, v5
	v_and_b32_e32 v21, 0xfffffc00, v5
	v_lshrrev_b32_e32 v22, 5, v20
	v_or_b32_e32 v21, v21, v22
	v_bfe_u32 v22, v20, 3, 2
	v_lshl_or_b32 v21, v22, 8, v21
	v_bfe_u32 v22, v20, 2, 1
	v_lshl_or_b32 v21, v22, 5, v21
	v_and_b32_e32 v22, 3, v20
	v_lshl_or_b32 v21, v22, 6, v21
	s_waitcnt vmcnt(6)
	v_cvt_pk_bf16_f32 v100, v56, v57
	v_cvt_pk_bf16_f32 v101, v58, v59
	v_cvt_pk_bf16_f32 v102, v60, v61
	v_cvt_pk_bf16_f32 v103, v62, v63
	v_lshlrev_b32_e32 v104, 4, v21
	global_store_dwordx4 v104, v[100:103], s[8:9]
	s_mov_b64 exec, s[22:23]
	v_and_b32_e32 v20, 0x3ff, v6
	v_and_b32_e32 v21, 0xfffffc00, v6
	v_lshrrev_b32_e32 v22, 5, v20
	v_or_b32_e32 v21, v21, v22
	v_bfe_u32 v22, v20, 3, 2
	v_lshl_or_b32 v21, v22, 8, v21
	v_bfe_u32 v22, v20, 2, 1
	v_lshl_or_b32 v21, v22, 5, v21
	v_and_b32_e32 v22, 3, v20
	v_lshl_or_b32 v21, v22, 6, v21
	s_waitcnt vmcnt(4)
	v_cvt_pk_bf16_f32 v106, v64, v65
	v_cvt_pk_bf16_f32 v107, v66, v67
	v_cvt_pk_bf16_f32 v108, v68, v69
	v_cvt_pk_bf16_f32 v109, v70, v71
	v_lshlrev_b32_e32 v110, 4, v21
	global_store_dwordx4 v110, v[106:109], s[8:9]
	s_mov_b64 exec, s[24:25]
	v_and_b32_e32 v20, 0x3ff, v7
	v_and_b32_e32 v21, 0xfffffc00, v7
	v_lshrrev_b32_e32 v22, 5, v20
	v_or_b32_e32 v21, v21, v22
	v_bfe_u32 v22, v20, 3, 2
	v_lshl_or_b32 v21, v22, 8, v21
	v_bfe_u32 v22, v20, 2, 1
	v_lshl_or_b32 v21, v22, 5, v21
	v_and_b32_e32 v22, 3, v20
	v_lshl_or_b32 v21, v22, 6, v21
	s_waitcnt vmcnt(2)
	v_cvt_pk_bf16_f32 v100, v72, v73
	v_cvt_pk_bf16_f32 v101, v74, v75
	v_cvt_pk_bf16_f32 v102, v76, v77
	v_cvt_pk_bf16_f32 v103, v78, v79
	v_lshlrev_b32_e32 v104, 4, v21
	global_store_dwordx4 v104, v[100:103], s[8:9]
	s_mov_b64 exec, s[26:27]
	v_and_b32_e32 v20, 0x3ff, v8
	v_and_b32_e32 v21, 0xfffffc00, v8
	v_lshrrev_b32_e32 v22, 5, v20
	v_or_b32_e32 v21, v21, v22
	v_bfe_u32 v22, v20, 3, 2
	v_lshl_or_b32 v21, v22, 8, v21
	v_bfe_u32 v22, v20, 2, 1
	v_lshl_or_b32 v21, v22, 5, v21
	v_and_b32_e32 v22, 3, v20
	v_lshl_or_b32 v21, v22, 6, v21
	s_waitcnt vmcnt(0)
	v_cvt_pk_bf16_f32 v106, v80, v81
	v_cvt_pk_bf16_f32 v107, v82, v83
	v_cvt_pk_bf16_f32 v108, v84, v85
	v_cvt_pk_bf16_f32 v109, v86, v87
	v_lshlrev_b32_e32 v110, 4, v21
	global_store_dwordx4 v110, v[106:109], s[8:9]
	s_mov_b64 exec, -1
	v_add_u32_e32 v0, 0xe0000, v0
	v_cmp_gt_u32_e32 vcc, s10, v0
	s_and_b64 vcc, exec, vcc
	s_cbranch_scc1 .Lsjd_loop6_0
